# store widening via v_permlane16_swap: in-proj (32 store blocks), FFN1 and PLE-proj epilogues now use dwordx4 stores
# speedup vs baseline: 1.0269x; 1.0269x over previous
; DI void inproj_tile8(const Params& P, const WsPtrs& W, int layer, int mt, int nt, unsigned char* smem) {
;     ...
;       const int tl = bj * 128 + wc * 32 + n * 16 + fr;
;       const float rv = rs[tl];
;       const float pos = (float)((m0 + tl) & 4095);
;       u16* rowp = W.Y + (size_t)(m0 + tl) * LDY;
; #pragma unroll
;       for (int ai = 0; ai < 2; ++ai) {
;         const int cb = n0 + ai * 128 + wr * 64;
;         f32x4v v[4];
; #pragma unroll
;         for (int m = 0; m < 4; ++m) { v[m] = acc[ai][bj][m][n]; v[m].x *= rv; v[m].y *= rv; v[m].z *= rv; v[m].w *= rv; }
;         if (qsec) {
;           const bool isq = cb < O_BK;
;           const float* gp = (isq ? P.in[I_DQG] : P.in[I_DKG]) + layer * 64;
;           float ss = 0.f;
; #pragma unroll
;           for (int m = 0; m < 4; ++m) ss += v[m].x * v[m].x + v[m].y * v[m].y + v[m].z * v[m].z + v[m].w * v[m].w;
;           ss += shx(ss, 16);
;           ss += shx(ss, 32);
;           const float sc = rsqrtf(ss * (1.f / 64.f) + EPSV) * (isq ? 0.125f * LOG2E : 1.f);
; #pragma unroll
;           for (int m = 0; m < 4; ++m) {
;             const f32x4 g4 = *(const f32x4*)(gp + m * 16 + fq * 4);
;             v[m].x *= sc * g4.x; v[m].y *= sc * g4.y; v[m].z *= sc * g4.z; v[m].w *= sc * g4.w;
;           }
;           const f32x4 fr4 = *(const f32x4*)(W.rope + (fq & 1) * 4);
;           float mine[4] = {v[0].x, v[0].y, v[0].z, v[0].w}, frq[4] = {fr4.x, fr4.y, fr4.z, fr4.w}, outv[4];
; #pragma unroll
;           for (int j = 0; j < 4; ++j) {
;             float c, sn; rot_cs(pos, frq[j], c, sn);
;             float oth = shx(mine[j], 32);
;             outv[j] = (fq < 2) ? (mine[j] * c - oth * sn) : (mine[j] * c + oth * sn);
;           }
;           v[0].x = outv[0]; v[0].y = outv[1]; v[0].z = outv[2]; v[0].w = outv[3];
;         } else if (rsec) {
;           const float ksc = (cb < O_DK) ? 1.f : 0.125f;
; #pragma unroll
;           for (int m = 0; m < 2; ++m) {
;             const f32x4 f4 = *(const f32x4*)(W.rope + 40 + m * 16 + fq * 4);
;             float frq[4] = {f4.x, f4.y, f4.z, f4.w};
;             float x1[4] = {v[m].x, v[m].y, v[m].z, v[m].w}, x2[4] = {v[m + 2].x, v[m + 2].y, v[m + 2].z, v[m + 2].w};
; #pragma unroll
;             for (int j = 0; j < 4; ++j) {
;               float c, sn; rot_cs(pos, frq[j], c, sn);
.LBB0_199:
	s_or_b64 exec, exec, s[4:5]
	v_mbcnt_lo_u32_b32 v196, -1, 0
	v_mbcnt_hi_u32_b32 v196, -1, v196
	v_bfe_u32 v196, v196, 4, 1
	v_mul_u32_u24_e32 v196, 24, v196
	v_mov_b32_e32 v197, 0
	s_cmp_lg_u32 s2, 8
	v_mov_b32_e32 v131, v250
	s_cselect_b64 s[12:13], -1, 0
	s_and_b32 s2, s25, -4
	s_cmp_eq_u32 s2, 24
	v_and_b32_e32 v0, 15, v131
	v_lshrrev_b32_e32 v130, 1, v131
	s_movk_i32 s2, 0x60
	v_and_or_b32 v159, v130, s2, v0
	v_ashrrev_i32_e32 v0, 2, v131
	v_and_b32_e32 v0, 0xffffffc0, v0
	v_add_u32_e32 v158, s10, v0
	v_lshl_add_u32 v0, v159, 2, 64
	v_add_u32_e32 v0, 0x24000, v0
	ds_read_b32 v130, v0
	v_mov_b32_e32 v0, s14
	s_movk_i32 s2, 0xf6f
	v_bitop3_b32 v0, v159, s2, v0 bitop3:0xc8
	v_bfe_u32 v132, v131, 4, 2
	v_cvt_f32_u32_e32 v161, v0
	s_cselect_b64 s[8:9], -1, 0
	v_lshlrev_b32_e32 v160, 2, v132
	v_cmp_gt_u32_e64 s[4:5], 2, v132
	s_waitcnt lgkmcnt(0)
	v_pk_mul_f32 v[132:133], v[114:115], v[130:131] op_sel_hi:[1,0]
	v_pk_mul_f32 v[114:115], v[126:127], v[130:131] op_sel_hi:[1,0]
	v_mov_b32_e32 v127, v118
	v_mov_b32_e32 v118, v123
	v_mov_b32_e32 v126, v122
	v_pk_mul_f32 v[136:137], v[118:119], v[130:131] op_sel_hi:[1,0]
	v_mov_b32_e32 v118, v124
	v_mov_b32_e32 v119, v120
	v_mov_b32_e32 v120, v125
	v_cndmask_b32_e64 v0, 0, 1, s[8:9]
	v_pk_mul_f32 v[134:135], v[116:117], v[130:131] op_sel_hi:[1,0]
	v_pk_mul_f32 v[116:117], v[128:129], v[130:131] op_sel_hi:[1,0]
	v_pk_mul_f32 v[126:127], v[126:127], v[130:131] op_sel_hi:[1,0]
	v_pk_mul_f32 v[128:129], v[118:119], v[130:131] op_sel_hi:[1,0]
	v_pk_mul_f32 v[124:125], v[120:121], v[130:131] op_sel_hi:[1,0]
	s_mov_b64 s[6:7], -1
	s_and_b64 vcc, exec, s[12:13]
	v_cmp_ne_u32_e64 s[74:75], 1, v0
	s_cbranch_vccz .LBB0_203
	s_and_b64 vcc, exec, s[74:75]
	s_cbranch_vccnz .LBB0_202
	v_readlane_b32 s6, v253, 58
	v_lshlrev_b32_e32 v152, 2, v160
	v_readlane_b32 s7, v253, 59
	v_mov_b32_e32 v150, v135
	v_mov_b32_e32 v151, v125
	s_movk_i32 s2, 0x1a00
	v_cmp_gt_i32_e32 vcc, s2, v158
	v_mov_b32_e32 v0, 0x3e000000
	global_load_dwordx4 v[118:121], v152, s[6:7]
	v_mov_b32_e32 v138, v127
	v_mov_b32_e32 v139, v137
	v_cndmask_b32_e64 v0, v0, 1.0, vcc
	v_pk_mov_b32 v[162:163], v[116:117], v[124:125] op_sel:[1,0]
	s_waitcnt vmcnt(0)
	v_mul_f32_e32 v142, v120, v161
	v_floor_f32_e32 v142, v142
	v_fma_f32 v120, v120, v161, -v142
	v_cos_f32_e32 v143, v120
	v_sin_f32_e32 v144, v120
	v_mul_f32_e32 v122, v118, v161
	v_mul_f32_e32 v123, v119, v161
	v_mul_f32_e32 v120, v134, v143
	v_mul_f32_e32 v146, v129, v143
	v_mul_f32_e32 v143, v121, v161
	v_floor_f32_e32 v143, v143
	v_fma_f32 v121, v121, v161, -v143
	v_mul_f32_e32 v142, v129, v144
	v_mul_f32_e32 v148, v134, v144
	v_cos_f32_e32 v144, v121
	v_sin_f32_e32 v145, v121
	v_floor_f32_e32 v122, v122
	v_floor_f32_e32 v123, v123
	v_fma_f32 v122, v118, v161, -v122
	v_fma_f32 v123, v119, v161, -v123
	v_cos_f32_e32 v118, v122
	v_sin_f32_e32 v122, v122
	v_cos_f32_e32 v119, v123
	v_sin_f32_e32 v123, v123
	v_pk_mul_f32 v[150:151], v[150:151], v[144:145]
	v_pk_mul_f32 v[140:141], v[138:139], v[122:123]
	v_mov_b32_e32 v121, v150
	v_mov_b32_e32 v143, v151
	v_mov_b32_e32 v150, v125
	v_mov_b32_e32 v151, v135
	v_pk_mul_f32 v[144:145], v[150:151], v[144:145]
	v_pk_mul_f32 v[122:123], v[132:133], v[122:123]
	v_mov_b32_e32 v147, v144
	v_mov_b32_e32 v149, v145
	v_pk_add_f32 v[120:121], v[120:121], v[142:143] neg_lo:[0,1] neg_hi:[0,1]
	v_pk_fma_f32 v[140:141], v[132:133], v[118:119], v[140:141] neg_lo:[0,0,1] neg_hi:[0,0,1]
	v_pk_mul_f32 v[142:143], v[0:1], v[120:121] op_sel_hi:[0,1]
	v_pk_fma_f32 v[118:119], v[138:139], v[118:119], v[122:123]
	v_pk_add_f32 v[120:121], v[146:147], v[148:149]
	v_pk_mul_f32 v[144:145], v[0:1], v[140:141] op_sel_hi:[0,1]
	v_pk_mul_f32 v[140:141], v[0:1], v[120:121] op_sel_hi:[0,1]
	v_pk_mul_f32 v[138:139], v[0:1], v[118:119] op_sel_hi:[0,1]
	global_load_dwordx4 v[118:121], v152, s[6:7] offset:64
	v_mov_b32_e32 v146, v126
	v_mov_b32_e32 v147, v136
	s_mov_b64 s[6:7], 0
	s_waitcnt vmcnt(0)
	v_mul_f32_e32 v122, v118, v161
	v_mul_f32_e32 v123, v119, v161
	v_floor_f32_e32 v122, v122
	v_floor_f32_e32 v123, v123
	v_fma_f32 v118, v118, v161, -v122
	v_fma_f32 v119, v119, v161, -v123
	v_cos_f32_e32 v122, v118
	v_sin_f32_e32 v118, v118
	v_cos_f32_e32 v123, v119
	v_sin_f32_e32 v119, v119
	s_nop 0
	v_pk_mul_f32 v[154:155], v[146:147], v[118:119]
	v_pk_mul_f32 v[148:149], v[114:115], v[118:119]
	v_mul_f32_e32 v118, v120, v161
	v_floor_f32_e32 v118, v118
	v_fma_f32 v118, v120, v161, -v118
	v_cos_f32_e32 v119, v118
	v_sin_f32_e32 v151, v118
	v_pk_fma_f32 v[154:155], v[114:115], v[122:123], v[154:155] neg_lo:[0,0,1] neg_hi:[0,0,1]
	v_pk_fma_f32 v[122:123], v[146:147], v[122:123], v[148:149]
	v_mul_f32_e32 v118, v116, v119
	v_mul_f32_e32 v150, v128, v119
	v_mul_f32_e32 v119, v121, v161
	v_floor_f32_e32 v119, v119
	v_fma_f32 v119, v121, v161, -v119
	v_cos_f32_e32 v156, v119
	v_sin_f32_e32 v157, v119
	v_mul_f32_e32 v120, v128, v151
	v_mul_f32_e32 v152, v116, v151
	v_pk_mul_f32 v[148:149], v[0:1], v[122:123] op_sel_hi:[0,1]
	v_pk_mul_f32 v[162:163], v[162:163], v[156:157]
	s_nop 0
	v_mov_b32_e32 v119, v162
	v_mov_b32_e32 v121, v163
	v_mov_b32_e32 v162, v124
	v_mov_b32_e32 v163, v117
	v_pk_mul_f32 v[156:157], v[162:163], v[156:157]
	v_pk_add_f32 v[120:121], v[118:119], v[120:121] neg_lo:[0,1] neg_hi:[0,1]
	v_mov_b32_e32 v151, v156
	v_mov_b32_e32 v153, v157
	v_pk_add_f32 v[146:147], v[150:151], v[152:153]
	v_pk_mul_f32 v[118:119], v[0:1], v[154:155] op_sel_hi:[0,1]
	v_pk_mul_f32 v[120:121], v[0:1], v[120:121] op_sel_hi:[0,1]
	v_pk_mul_f32 v[146:147], v[0:1], v[146:147] op_sel_hi:[0,1]
	s_branch .LBB0_203

; DI u32 pack2(float a, float b) { f2_t v = {a, b}; bf2_t r = __builtin_convertvector(v, bf2_t); return __builtin_bit_cast(u32, r); }
; DI void inproj_tile8(const Params& P, const WsPtrs& W, int layer, int mt, int nt, unsigned char* smem) {
;     ...
; #pragma unroll
;         for (int m = 0; m < 4; ++m) {
;           const int f = cb + m * 16 + fq * 4;
;           if (f < O_END) {
;             u32x2 o2; o2.x = pack2(v[m].x, v[m].y); o2.y = pack2(v[m].z, v[m].w);
;             *(u32x2*)(rowp + f) = o2;
;           }
;         }
.LBB0_205:
	v_or_b32_e32 v0, s14, v159
	v_mov_b64_e32 v[114:115], s[52:53]
	v_mad_i64_i32 v[116:117], s[6:7], v0, s33, v[114:115]
	v_or_b32_e32 v114, v160, v158
	s_movk_i32 s2, 0x32c0
	v_ashrrev_i32_e32 v115, 31, v114
	v_cmp_gt_i32_e64 s[8:9], s2, v114
	s_mov_b64 s[6:7], exec
	s_nop 0
	v_writelane_b32 v255, s8, 26
	s_nop 1
	v_writelane_b32 v255, s9, 27
	s_and_b64 s[8:9], s[6:7], s[8:9]
	s_mov_b64 exec, s[8:9]
	s_cbranch_execz .LBB0_207
	v_cvt_pk_bf16_f32 v200, v144, v145
	v_cvt_pk_bf16_f32 v201, v142, v143
	v_lshl_add_u64 v[126:127], v[114:115], 1, v[116:117]
	s_nop 0
.LBB0_207:
	s_or_b64 exec, exec, s[6:7]
	v_or_b32_e32 v0, 16, v114
	v_cmp_gt_i32_e64 s[8:9], s2, v0
	s_mov_b64 s[80:81], s[8:9]
	s_and_saveexec_b64 s[6:7], s[8:9]
	s_cbranch_execz .LBB0_209
	v_cvt_pk_bf16_f32 v202, v118, v119
	v_cvt_pk_bf16_f32 v203, v120, v121
	v_lshl_add_u64 v[120:121], v[114:115], 1, v[116:117]
	v_lshl_add_u64 v[120:121], v[120:121], 0, v[196:197]
	s_nop 1
	v_permlane16_swap_b32_e32 v200, v202
	v_permlane16_swap_b32_e32 v201, v203
	global_store_dwordx4 v[120:121], v[200:203], off
.LBB0_209:
	s_or_b64 exec, exec, s[6:7]
	v_or_b32_e32 v0, 32, v114
	v_cmp_gt_i32_e64 s[8:9], s2, v0
	s_mov_b64 s[70:71], s[8:9]
	s_and_saveexec_b64 s[6:7], s[8:9]
	s_cbranch_execz .LBB0_211
	v_cvt_pk_bf16_f32 v204, v138, v139
	v_cvt_pk_bf16_f32 v205, v140, v141
	v_lshl_add_u64 v[120:121], v[114:115], 1, v[116:117]
	s_nop 0
.LBB0_211:
	s_or_b64 exec, exec, s[6:7]
	v_or_b32_e32 v0, 48, v114
	v_cmp_gt_i32_e64 s[6:7], s2, v0
	s_and_saveexec_b64 s[8:9], s[6:7]
	s_cbranch_execz .LBB0_213
	v_cvt_pk_bf16_f32 v206, v148, v149
	v_cvt_pk_bf16_f32 v207, v146, v147
	v_lshl_add_u64 v[120:121], v[114:115], 1, v[116:117]
	v_lshl_add_u64 v[120:121], v[120:121], 0, v[196:197]
	s_nop 1
	v_permlane16_swap_b32_e32 v204, v206
	v_permlane16_swap_b32_e32 v205, v207
	global_store_dwordx4 v[120:121], v[204:207], off offset:64

; DI u32 pack2(float a, float b) { f2_t v = {a, b}; bf2_t r = __builtin_convertvector(v, bf2_t); return __builtin_bit_cast(u32, r); }
; DI void inproj_tile8(const Params& P, const WsPtrs& W, int layer, int mt, int nt, unsigned char* smem) {
;     ...
; #pragma unroll
;         for (int m = 0; m < 4; ++m) {
;           const int f = cb + m * 16 + fq * 4;
;           if (f < O_END) {
;             u32x2 o2; o2.x = pack2(v[m].x, v[m].y); o2.y = pack2(v[m].z, v[m].w);
;             *(u32x2*)(rowp + f) = o2;
;           }
;         }
.LBB0_218:
	v_or_b32_e32 v102, v146, v160
	s_movk_i32 s2, 0x32c0
	v_cmp_gt_i32_e64 s[12:13], s2, v102
	v_ashrrev_i32_e32 v103, 31, v102
	s_mov_b64 s[26:27], s[12:13]
	s_and_saveexec_b64 s[8:9], s[12:13]
	s_cbranch_execz .LBB0_220
	v_cvt_pk_bf16_f32 v200, v136, v137
	v_cvt_pk_bf16_f32 v201, v104, v105
	v_lshl_add_u64 v[104:105], v[102:103], 1, v[116:117]
	s_nop 0
.LBB0_220:
	s_or_b64 exec, exec, s[8:9]
	v_or_b32_e32 v0, 16, v102
	v_cmp_gt_i32_e64 s[8:9], s2, v0
	s_and_saveexec_b64 s[12:13], s[8:9]
	s_cbranch_execz .LBB0_222
	v_cvt_pk_bf16_f32 v202, v98, v99
	v_cvt_pk_bf16_f32 v203, v100, v101
	v_lshl_add_u64 v[100:101], v[102:103], 1, v[116:117]
	v_lshl_add_u64 v[100:101], v[100:101], 0, v[196:197]
	s_nop 1
	v_permlane16_swap_b32_e32 v200, v202
	v_permlane16_swap_b32_e32 v201, v203
	global_store_dwordx4 v[100:101], v[200:203], off
.LBB0_222:
	s_or_b64 exec, exec, s[12:13]
	v_or_b32_e32 v0, 32, v102
	v_cmp_gt_i32_e64 s[18:19], s2, v0
	s_and_saveexec_b64 s[12:13], s[18:19]
	s_cbranch_execz .LBB0_224
	v_cvt_pk_bf16_f32 v204, v112, v113
	v_cvt_pk_bf16_f32 v205, v110, v111
	v_lshl_add_u64 v[100:101], v[102:103], 1, v[116:117]
	s_nop 0
.LBB0_224:
	s_or_b64 exec, exec, s[12:13]
	v_or_b32_e32 v0, 48, v102
	v_cmp_gt_i32_e64 s[12:13], s2, v0
	s_and_saveexec_b64 s[20:21], s[12:13]
	s_cbranch_execz .LBB0_226
	v_cvt_pk_bf16_f32 v206, v134, v135
	v_cvt_pk_bf16_f32 v207, v132, v133
	v_lshl_add_u64 v[100:101], v[102:103], 1, v[116:117]
	v_lshl_add_u64 v[100:101], v[100:101], 0, v[196:197]
	s_nop 1
	v_permlane16_swap_b32_e32 v204, v206
	v_permlane16_swap_b32_e32 v205, v207
	global_store_dwordx4 v[100:101], v[204:207], off offset:64

; DI u32 pack2(float a, float b) { f2_t v = {a, b}; bf2_t r = __builtin_convertvector(v, bf2_t); return __builtin_bit_cast(u32, r); }
; DI void inproj_tile8(const Params& P, const WsPtrs& W, int layer, int mt, int nt, unsigned char* smem) {
;     ...
; #pragma unroll
;         for (int m = 0; m < 4; ++m) {
;           const int f = cb + m * 16 + fq * 4;
;           if (f < O_END) {
;             u32x2 o2; o2.x = pack2(v[m].x, v[m].y); o2.y = pack2(v[m].z, v[m].w);
;             *(u32x2*)(rowp + f) = o2;
;           }
;         }
.LBB0_235:
	v_cvt_pk_bf16_f32 v206, v118, v119
	v_cvt_pk_bf16_f32 v207, v116, v117
	v_lshl_add_u64 v[84:85], v[114:115], 1, v[86:87]
	v_lshl_add_u64 v[84:85], v[84:85], 0, v[196:197]
	s_nop 1
	v_permlane16_swap_b32_e32 v204, v206
	v_permlane16_swap_b32_e32 v205, v207
	global_store_dwordx4 v[84:85], v[204:207], off offset:64

; DI u32 pack2(float a, float b) { f2_t v = {a, b}; bf2_t r = __builtin_convertvector(v, bf2_t); return __builtin_bit_cast(u32, r); }
; DI void inproj_tile8(const Params& P, const WsPtrs& W, int layer, int mt, int nt, unsigned char* smem) {
;     ...
; #pragma unroll
;         for (int m = 0; m < 4; ++m) {
;           const int f = cb + m * 16 + fq * 4;
;           if (f < O_END) {
;             u32x2 o2; o2.x = pack2(v[m].x, v[m].y); o2.y = pack2(v[m].z, v[m].w);
;             *(u32x2*)(rowp + f) = o2;
;           }
;         }
.LBB0_242:
	v_cvt_pk_bf16_f32 v206, v98, v99
	v_cvt_pk_bf16_f32 v207, v96, v97
	v_lshl_add_u64 v[68:69], v[102:103], 1, v[86:87]
	v_lshl_add_u64 v[68:69], v[68:69], 0, v[196:197]
	s_nop 1
	v_permlane16_swap_b32_e32 v204, v206
	v_permlane16_swap_b32_e32 v205, v207
	global_store_dwordx4 v[68:69], v[204:207], off offset:64

; DI u32 pack2(float a, float b) { f2_t v = {a, b}; bf2_t r = __builtin_convertvector(v, bf2_t); return __builtin_bit_cast(u32, r); }
; DI void inproj_tile8(const Params& P, const WsPtrs& W, int layer, int mt, int nt, unsigned char* smem) {
;     ...
; #pragma unroll
;         for (int m = 0; m < 4; ++m) {
;           const int f = cb + m * 16 + fq * 4;
;           if (f < O_END) {
;             u32x2 o2; o2.x = pack2(v[m].x, v[m].y); o2.y = pack2(v[m].z, v[m].w);
;             *(u32x2*)(rowp + f) = o2;
;           }
;         }
.LBB0_252:
	v_cvt_pk_bf16_f32 v206, v82, v83
	v_cvt_pk_bf16_f32 v207, v80, v81
	v_lshl_add_u64 v[52:53], v[114:115], 1, v[54:55]
	v_lshl_add_u64 v[52:53], v[52:53], 0, v[196:197]
	s_nop 1
	v_permlane16_swap_b32_e32 v204, v206
	v_permlane16_swap_b32_e32 v205, v207
	global_store_dwordx4 v[52:53], v[204:207], off offset:64

; DI u32 pack2(float a, float b) { f2_t v = {a, b}; bf2_t r = __builtin_convertvector(v, bf2_t); return __builtin_bit_cast(u32, r); }
; DI void inproj_tile8(const Params& P, const WsPtrs& W, int layer, int mt, int nt, unsigned char* smem) {
;     ...
; #pragma unroll
;         for (int m = 0; m < 4; ++m) {
;           const int f = cb + m * 16 + fq * 4;
;           if (f < O_END) {
;             u32x2 o2; o2.x = pack2(v[m].x, v[m].y); o2.y = pack2(v[m].z, v[m].w);
;             *(u32x2*)(rowp + f) = o2;
;           }
;         }
.LBB0_259:
	v_cvt_pk_bf16_f32 v206, v66, v67
	v_cvt_pk_bf16_f32 v207, v64, v65
	v_lshl_add_u64 v[36:37], v[102:103], 1, v[54:55]
	v_lshl_add_u64 v[36:37], v[36:37], 0, v[196:197]
	s_nop 1
	v_permlane16_swap_b32_e32 v204, v206
	v_permlane16_swap_b32_e32 v205, v207
	global_store_dwordx4 v[36:37], v[204:207], off offset:64

; DI u32 pack2(float a, float b) { f2_t v = {a, b}; bf2_t r = __builtin_convertvector(v, bf2_t); return __builtin_bit_cast(u32, r); }
; DI void inproj_tile8(const Params& P, const WsPtrs& W, int layer, int mt, int nt, unsigned char* smem) {
;     ...
; #pragma unroll
;         for (int m = 0; m < 4; ++m) {
;           const int f = cb + m * 16 + fq * 4;
;           if (f < O_END) {
;             u32x2 o2; o2.x = pack2(v[m].x, v[m].y); o2.y = pack2(v[m].z, v[m].w);
;             *(u32x2*)(rowp + f) = o2;
;           }
;         }
.LBB0_265:
	v_or_b32_e32 v0, s14, v35
	v_mov_b64_e32 v[22:23], s[52:53]
	v_mad_i64_i32 v[22:23], s[20:21], v0, s33, v[22:23]
	s_mov_b64 s[20:21], exec
	v_readlane_b32 s28, v255, 26
	v_readlane_b32 s29, v255, 27
	s_and_b64 s[28:29], s[20:21], s[28:29]
	s_mov_b64 exec, s[28:29]
	s_cbranch_execz .LBB0_267
	v_cvt_pk_bf16_f32 v200, v52, v53
	v_cvt_pk_bf16_f32 v201, v24, v25
	v_lshl_add_u64 v[24:25], v[114:115], 1, v[22:23]
	s_nop 0

; DI u32 pack2(float a, float b) { f2_t v = {a, b}; bf2_t r = __builtin_convertvector(v, bf2_t); return __builtin_bit_cast(u32, r); }
; DI void inproj_tile8(const Params& P, const WsPtrs& W, int layer, int mt, int nt, unsigned char* smem) {
;     ...
; #pragma unroll
;         for (int m = 0; m < 4; ++m) {
;           const int f = cb + m * 16 + fq * 4;
;           if (f < O_END) {
;             u32x2 o2; o2.x = pack2(v[m].x, v[m].y); o2.y = pack2(v[m].z, v[m].w);
;             *(u32x2*)(rowp + f) = o2;
;           }
;         }
.LBB0_270:
	v_cvt_pk_bf16_f32 v206, v50, v51
	v_cvt_pk_bf16_f32 v207, v48, v49
	v_lshl_add_u64 v[20:21], v[114:115], 1, v[22:23]
	v_lshl_add_u64 v[20:21], v[20:21], 0, v[196:197]
	s_nop 1
	v_permlane16_swap_b32_e32 v204, v206
	v_permlane16_swap_b32_e32 v205, v207
	global_store_dwordx4 v[20:21], v[204:207], off offset:64

; DI u32 pack2(float a, float b) { f2_t v = {a, b}; bf2_t r = __builtin_convertvector(v, bf2_t); return __builtin_bit_cast(u32, r); }
; DI void inproj_tile8(const Params& P, const WsPtrs& W, int layer, int mt, int nt, unsigned char* smem) {
;     ...
; #pragma unroll
;         for (int m = 0; m < 4; ++m) {
;           const int f = cb + m * 16 + fq * 4;
;           if (f < O_END) {
;             u32x2 o2; o2.x = pack2(v[m].x, v[m].y); o2.y = pack2(v[m].z, v[m].w);
;             *(u32x2*)(rowp + f) = o2;
;           }
;         }
.LBB0_277:
	v_cvt_pk_bf16_f32 v206, v34, v35
	v_cvt_pk_bf16_f32 v207, v32, v33
	v_lshl_add_u64 v[4:5], v[102:103], 1, v[22:23]
	v_lshl_add_u64 v[4:5], v[4:5], 0, v[196:197]
	s_nop 1
	v_permlane16_swap_b32_e32 v204, v206
	v_permlane16_swap_b32_e32 v205, v207
	global_store_dwordx4 v[4:5], v[204:207], off offset:64

; DI u32 pack2(float a, float b) { f2_t v = {a, b}; bf2_t r = __builtin_convertvector(v, bf2_t); return __builtin_bit_cast(u32, r); }
; DI void inproj_tile8(const Params& P, const WsPtrs& W, int layer, int mt, int nt, unsigned char* smem) {
;     ...
; #pragma unroll
;         for (int m = 0; m < 4; ++m) {
;           const int f = cb + m * 16 + fq * 4;
;           if (f < O_END) {
;             u32x2 o2; o2.x = pack2(v[m].x, v[m].y); o2.y = pack2(v[m].z, v[m].w);
;             *(u32x2*)(rowp + f) = o2;
;           }
;         }
.LBB0_286:
	v_cvt_pk_bf16_f32 v200, v120, v121
	v_cvt_pk_bf16_f32 v201, v88, v89
	v_lshl_add_u64 v[88:89], v[114:115], 1, v[86:87]
	s_nop 0
	s_or_b64 exec, exec, s[20:21]
	s_and_saveexec_b64 s[20:21], s[80:81]
	s_cbranch_execz .LBB0_233
.LBB0_287:
	v_cvt_pk_bf16_f32 v202, v82, v83
	v_cvt_pk_bf16_f32 v203, v84, v85
	v_lshl_add_u64 v[84:85], v[114:115], 1, v[86:87]
	v_lshl_add_u64 v[84:85], v[84:85], 0, v[196:197]
	s_nop 1
	v_permlane16_swap_b32_e32 v200, v202
	v_permlane16_swap_b32_e32 v201, v203
	global_store_dwordx4 v[84:85], v[200:203], off
	s_or_b64 exec, exec, s[20:21]
	s_and_saveexec_b64 s[20:21], s[70:71]
	s_cbranch_execz .LBB0_234
.LBB0_288:
	v_cvt_pk_bf16_f32 v204, v96, v97
	v_cvt_pk_bf16_f32 v205, v94, v95
	v_lshl_add_u64 v[84:85], v[114:115], 1, v[86:87]
	s_nop 0
	s_or_b64 exec, exec, s[20:21]
	s_and_saveexec_b64 s[20:21], s[6:7]
	s_cbranch_execnz .LBB0_235
	s_branch .LBB0_236

; DI u32 pack2(float a, float b) { f2_t v = {a, b}; bf2_t r = __builtin_convertvector(v, bf2_t); return __builtin_bit_cast(u32, r); }
; DI void inproj_tile8(const Params& P, const WsPtrs& W, int layer, int mt, int nt, unsigned char* smem) {
;     ...
; #pragma unroll
;         for (int m = 0; m < 4; ++m) {
;           const int f = cb + m * 16 + fq * 4;
;           if (f < O_END) {
;             u32x2 o2; o2.x = pack2(v[m].x, v[m].y); o2.y = pack2(v[m].z, v[m].w);
;             *(u32x2*)(rowp + f) = o2;
;           }
;         }
.LBB0_291:
	v_cvt_pk_bf16_f32 v200, v84, v85
	v_cvt_pk_bf16_f32 v201, v56, v57
	v_lshl_add_u64 v[56:57], v[114:115], 1, v[54:55]
	s_nop 0
	s_or_b64 exec, exec, s[20:21]
	s_and_saveexec_b64 s[20:21], s[80:81]
	s_cbranch_execz .LBB0_250
.LBB0_292:
	v_cvt_pk_bf16_f32 v202, v50, v51
	v_cvt_pk_bf16_f32 v203, v52, v53
	v_lshl_add_u64 v[52:53], v[114:115], 1, v[54:55]
	v_lshl_add_u64 v[52:53], v[52:53], 0, v[196:197]
	s_nop 1
	v_permlane16_swap_b32_e32 v200, v202
	v_permlane16_swap_b32_e32 v201, v203
	global_store_dwordx4 v[52:53], v[200:203], off
	s_or_b64 exec, exec, s[20:21]
	s_and_saveexec_b64 s[20:21], s[70:71]
	s_cbranch_execz .LBB0_251
.LBB0_293:
	v_cvt_pk_bf16_f32 v204, v64, v65
	v_cvt_pk_bf16_f32 v205, v62, v63
	v_lshl_add_u64 v[52:53], v[114:115], 1, v[54:55]
	s_nop 0
	s_or_b64 exec, exec, s[20:21]
	s_and_saveexec_b64 s[20:21], s[6:7]
	s_cbranch_execnz .LBB0_252
	s_branch .LBB0_253

; DI u32 pack2(float a, float b) { f2_t v = {a, b}; bf2_t r = __builtin_convertvector(v, bf2_t); return __builtin_bit_cast(u32, r); }
; DI void inproj_tile8(const Params& P, const WsPtrs& W, int layer, int mt, int nt, unsigned char* smem) {
;     ...
; #pragma unroll
;         for (int m = 0; m < 4; ++m) {
;           const int f = cb + m * 16 + fq * 4;
;           if (f < O_END) {
;             u32x2 o2; o2.x = pack2(v[m].x, v[m].y); o2.y = pack2(v[m].z, v[m].w);
;             *(u32x2*)(rowp + f) = o2;
;           }
;         }
.LBB0_296:
	v_cvt_pk_bf16_f32 v202, v18, v19
	v_cvt_pk_bf16_f32 v203, v20, v21
	v_lshl_add_u64 v[20:21], v[114:115], 1, v[22:23]
	v_lshl_add_u64 v[20:21], v[20:21], 0, v[196:197]
	s_nop 1
	v_permlane16_swap_b32_e32 v200, v202
	v_permlane16_swap_b32_e32 v201, v203
	global_store_dwordx4 v[20:21], v[200:203], off
	s_or_b64 exec, exec, s[20:21]
	s_and_saveexec_b64 s[20:21], s[70:71]
	s_cbranch_execz .LBB0_269
.LBB0_297:
	v_cvt_pk_bf16_f32 v204, v32, v33
	v_cvt_pk_bf16_f32 v205, v30, v31
	v_lshl_add_u64 v[20:21], v[114:115], 1, v[22:23]
	s_nop 0
	s_or_b64 exec, exec, s[20:21]
	s_and_saveexec_b64 s[20:21], s[6:7]
	s_cbranch_execnz .LBB0_270
	s_branch .LBB0_271

; DI u32 pack2(float a, float b) { f2_t v = {a, b}; bf2_t r = __builtin_convertvector(v, bf2_t); return __builtin_bit_cast(u32, r); }
; DI void inproj_tile8(const Params& P, const WsPtrs& W, int layer, int mt, int nt, unsigned char* smem) {
;     ...
; #pragma unroll
;         for (int m = 0; m < 4; ++m) {
;           const int f = cb + m * 16 + fq * 4;
;           if (f < O_END) {
;             u32x2 o2; o2.x = pack2(v[m].x, v[m].y); o2.y = pack2(v[m].z, v[m].w);
;             *(u32x2*)(rowp + f) = o2;
;           }
;         }
.LBB0_306:
	v_cvt_pk_bf16_f32 v200, v72, v73
	v_cvt_pk_bf16_f32 v201, v70, v71
	v_lshl_add_u64 v[70:71], v[102:103], 1, v[86:87]
	s_nop 0
	s_or_b64 exec, exec, s[20:21]
	s_and_saveexec_b64 s[20:21], s[8:9]
	s_cbranch_execz .LBB0_240
.LBB0_307:
	v_cvt_pk_bf16_f32 v202, v66, v67
	v_cvt_pk_bf16_f32 v203, v68, v69
	v_lshl_add_u64 v[68:69], v[102:103], 1, v[86:87]
	v_lshl_add_u64 v[68:69], v[68:69], 0, v[196:197]
	s_nop 1
	v_permlane16_swap_b32_e32 v200, v202
	v_permlane16_swap_b32_e32 v201, v203
	global_store_dwordx4 v[68:69], v[200:203], off
	s_or_b64 exec, exec, s[20:21]
	s_and_saveexec_b64 s[20:21], s[18:19]
	s_cbranch_execz .LBB0_241
.LBB0_308:
	v_cvt_pk_bf16_f32 v204, v80, v81
	v_cvt_pk_bf16_f32 v205, v78, v79
	v_lshl_add_u64 v[68:69], v[102:103], 1, v[86:87]
	s_nop 0
	s_or_b64 exec, exec, s[20:21]
	s_and_saveexec_b64 s[20:21], s[12:13]
	s_cbranch_execnz .LBB0_242
	s_branch .LBB0_243

; DI u32 pack2(float a, float b) { f2_t v = {a, b}; bf2_t r = __builtin_convertvector(v, bf2_t); return __builtin_bit_cast(u32, r); }
; DI void inproj_tile8(const Params& P, const WsPtrs& W, int layer, int mt, int nt, unsigned char* smem) {
;     ...
; #pragma unroll
;         for (int m = 0; m < 4; ++m) {
;           const int f = cb + m * 16 + fq * 4;
;           if (f < O_END) {
;             u32x2 o2; o2.x = pack2(v[m].x, v[m].y); o2.y = pack2(v[m].z, v[m].w);
;             *(u32x2*)(rowp + f) = o2;
;           }
;         }
.LBB0_311:
	v_cvt_pk_bf16_f32 v200, v40, v41
	v_cvt_pk_bf16_f32 v201, v38, v39
	v_lshl_add_u64 v[38:39], v[102:103], 1, v[54:55]
	s_nop 0
	s_or_b64 exec, exec, s[20:21]
	s_and_saveexec_b64 s[20:21], s[8:9]
	s_cbranch_execz .LBB0_257
.LBB0_312:
	v_cvt_pk_bf16_f32 v202, v34, v35
	v_cvt_pk_bf16_f32 v203, v36, v37
	v_lshl_add_u64 v[36:37], v[102:103], 1, v[54:55]
	v_lshl_add_u64 v[36:37], v[36:37], 0, v[196:197]
	s_nop 1
	v_permlane16_swap_b32_e32 v200, v202
	v_permlane16_swap_b32_e32 v201, v203
	global_store_dwordx4 v[36:37], v[200:203], off
	s_or_b64 exec, exec, s[20:21]
	s_and_saveexec_b64 s[20:21], s[18:19]
	s_cbranch_execz .LBB0_258
.LBB0_313:
	v_cvt_pk_bf16_f32 v204, v48, v49
	v_cvt_pk_bf16_f32 v205, v46, v47
	v_lshl_add_u64 v[36:37], v[102:103], 1, v[54:55]
	s_nop 0
	s_or_b64 exec, exec, s[20:21]
	s_and_saveexec_b64 s[20:21], s[12:13]
	s_cbranch_execnz .LBB0_259
	s_branch .LBB0_260

; DI u32 pack2(float a, float b) { f2_t v = {a, b}; bf2_t r = __builtin_convertvector(v, bf2_t); return __builtin_bit_cast(u32, r); }
; DI void inproj_tile8(const Params& P, const WsPtrs& W, int layer, int mt, int nt, unsigned char* smem) {
;     ...
; #pragma unroll
;         for (int m = 0; m < 4; ++m) {
;           const int f = cb + m * 16 + fq * 4;
;           if (f < O_END) {
;             u32x2 o2; o2.x = pack2(v[m].x, v[m].y); o2.y = pack2(v[m].z, v[m].w);
;             *(u32x2*)(rowp + f) = o2;
;           }
;         }
.LBB0_316:
	v_cvt_pk_bf16_f32 v200, v8, v9
	v_cvt_pk_bf16_f32 v201, v6, v7
	v_lshl_add_u64 v[6:7], v[102:103], 1, v[22:23]
	s_nop 0
	s_or_b64 exec, exec, s[4:5]
	s_and_saveexec_b64 s[4:5], s[8:9]
	s_cbranch_execz .LBB0_275
.LBB0_317:
	v_cvt_pk_bf16_f32 v202, v2, v3
	v_cvt_pk_bf16_f32 v203, v4, v5
	v_lshl_add_u64 v[4:5], v[102:103], 1, v[22:23]
	v_lshl_add_u64 v[4:5], v[4:5], 0, v[196:197]
	s_nop 1
	v_permlane16_swap_b32_e32 v200, v202
	v_permlane16_swap_b32_e32 v201, v203
	global_store_dwordx4 v[4:5], v[200:203], off
	s_or_b64 exec, exec, s[4:5]
	s_and_saveexec_b64 s[4:5], s[18:19]
	s_cbranch_execz .LBB0_276
.LBB0_318:
	v_cvt_pk_bf16_f32 v204, v16, v17
	v_cvt_pk_bf16_f32 v205, v14, v15
	v_lshl_add_u64 v[4:5], v[102:103], 1, v[22:23]
	s_nop 0
	s_or_b64 exec, exec, s[4:5]
	s_and_saveexec_b64 s[4:5], s[12:13]
	s_cbranch_execnz .LBB0_277
	s_branch .LBB0_278

; DI u32 pack2(float a, float b) { f2_t v = {a, b}; bf2_t r = __builtin_convertvector(v, bf2_t); return __builtin_bit_cast(u32, r); }
; DI void ffn1_tile8(const WsPtrs& W, int layer, int mt, int nt, unsigned char* smem) {
;     ...
;       const int tl = bj * 128 + wc * 32 + n * 16 + fr;
;       const float rv = rs[tl];
;       u16* rowp = W.H1 + (size_t)(m0 + tl) * 4096 + n0 + wr * 64 + fq * 4;
; #pragma unroll
;       for (int ai = 0; ai < 2; ++ai)
; #pragma unroll
;         for (int m = 0; m < 4; ++m) {
;           f32x4v v = acc[ai][bj][m][n];
;           float a0 = fmaxf(v.x * rv, 0.f), a1 = fmaxf(v.y * rv, 0.f), a2 = fmaxf(v.z * rv, 0.f), a3 = fmaxf(v.w * rv, 0.f);
;           u32x2 o2; o2.x = pack2(a0 * a0, a1 * a1); o2.y = pack2(a2 * a2, a3 * a3);
;           *(u32x2*)(rowp + ai * 128 + m * 16) = o2;
;         }
.LBB0_905:
	s_or_b64 exec, exec, s[8:9]
	v_mbcnt_lo_u32_b32 v204, -1, 0
	v_mbcnt_hi_u32_b32 v204, -1, v204
	v_bfe_u32 v204, v204, 4, 1
	v_mul_u32_u24_e32 v204, 24, v204
	v_mov_b32_e32 v205, 0
	v_mov_b32_e32 v0, v250
	s_add_u32 s8, s62, s18
	s_movk_i32 s7, 0x60
	v_and_b32_e32 v130, 15, v0
	v_lshrrev_b32_e32 v133, 1, v0
	s_addc_u32 s9, s63, s19
	v_and_or_b32 v132, v133, s7, v130
	v_ashrrev_i32_e32 v0, 2, v0
	s_add_i32 s7, 64, 0x24000
	v_and_b32_e32 v130, 0xffffffc0, v0
	v_lshl_add_u32 v0, v132, 2, s7
	ds_read_b32 v136, v0
	v_or_b32_e32 v134, s6, v132
	v_ashrrev_i32_e32 v135, 31, v134
	v_lshlrev_b64 v[134:135], 13, v[134:135]
	v_ashrrev_i32_e32 v131, 31, v130
	v_lshl_add_u64 v[134:135], s[8:9], 0, v[134:135]
	s_lshl_b64 s[10:11], s[10:11], 1
	s_waitcnt lgkmcnt(0)
	v_mul_f32_e32 v98, v98, v136
	v_mul_f32_e32 v99, v99, v136
	v_mul_f32_e32 v100, v100, v136
	v_mul_f32_e32 v101, v101, v136
	v_lshl_add_u64 v[134:135], v[134:135], 0, s[10:11]
	v_lshlrev_b64 v[130:131], 1, v[130:131]
	v_max_f32_e32 v98, 0, v98
	v_max_f32_e32 v99, 0, v99
	v_max_f32_e32 v100, 0, v100
	v_max_f32_e32 v101, 0, v101
	v_lshl_add_u64 v[134:135], v[134:135], 0, v[130:131]
	v_and_b32_e32 v0, 24, v133
	v_pk_mul_f32 v[98:99], v[98:99], v[98:99]
	v_pk_mul_f32 v[100:101], v[100:101], v[100:101]
	v_lshl_add_u64 v[134:135], v[134:135], 0, v[0:1]
	v_cvt_pk_bf16_f32 v142, v98, v99
	v_cvt_pk_bf16_f32 v143, v100, v101
	s_nop 0
	v_mul_f32_e32 v98, v126, v136
	v_mul_f32_e32 v99, v127, v136
	v_mul_f32_e32 v100, v128, v136
	v_mul_f32_e32 v101, v129, v136
	v_max_f32_e32 v98, 0, v98
	v_max_f32_e32 v99, 0, v99
	v_max_f32_e32 v100, 0, v100
	v_max_f32_e32 v101, 0, v101
	v_pk_mul_f32 v[98:99], v[98:99], v[98:99]
	v_pk_mul_f32 v[100:101], v[100:101], v[100:101]
	v_cvt_pk_bf16_f32 v144, v98, v99
	v_cvt_pk_bf16_f32 v145, v100, v101
	s_nop 0
	v_mul_f32_e32 v98, v118, v136
	v_mul_f32_e32 v99, v119, v136
	v_mul_f32_e32 v100, v120, v136
	v_mul_f32_e32 v101, v121, v136
	v_max_f32_e32 v98, 0, v98
	v_max_f32_e32 v99, 0, v99
	v_max_f32_e32 v100, 0, v100
	v_max_f32_e32 v101, 0, v101
	v_pk_mul_f32 v[98:99], v[98:99], v[98:99]
	v_pk_mul_f32 v[100:101], v[100:101], v[100:101]
	v_cvt_pk_bf16_f32 v146, v98, v99
	v_cvt_pk_bf16_f32 v147, v100, v101
	v_lshl_add_u64 v[206:207], v[134:135], 0, v[204:205]
	s_nop 1
	v_permlane16_swap_b32_e32 v144, v146
	v_permlane16_swap_b32_e32 v145, v147
	global_store_dwordx4 v[206:207], v[144:147], off offset:256
	v_mul_f32_e32 v98, v110, v136
	v_mul_f32_e32 v99, v111, v136
	v_mul_f32_e32 v100, v112, v136
	v_mul_f32_e32 v101, v113, v136
	v_max_f32_e32 v98, 0, v98
	v_max_f32_e32 v99, 0, v99
	v_max_f32_e32 v100, 0, v100
	v_max_f32_e32 v101, 0, v101
	v_pk_mul_f32 v[98:99], v[98:99], v[98:99]
	v_pk_mul_f32 v[100:101], v[100:101], v[100:101]
	v_cvt_pk_bf16_f32 v148, v98, v99
	v_cvt_pk_bf16_f32 v149, v100, v101
	s_nop 0
	v_mul_f32_e32 v98, v102, v136
	v_mul_f32_e32 v99, v103, v136
	v_mul_f32_e32 v100, v104, v136
	v_mul_f32_e32 v101, v105, v136
	v_max_f32_e32 v98, 0, v98
	v_max_f32_e32 v99, 0, v99
	v_max_f32_e32 v100, 0, v100
	v_max_f32_e32 v101, 0, v101
	v_pk_mul_f32 v[98:99], v[98:99], v[98:99]
	v_pk_mul_f32 v[100:101], v[100:101], v[100:101]
	v_cvt_pk_bf16_f32 v150, v98, v99
	v_cvt_pk_bf16_f32 v151, v100, v101
	v_lshl_add_u64 v[206:207], v[134:135], 0, v[204:205]
	s_nop 1
	v_permlane16_swap_b32_e32 v148, v150
	v_permlane16_swap_b32_e32 v149, v151
	global_store_dwordx4 v[206:207], v[148:151], off offset:320
	v_or_b32_e32 v98, 16, v132
	v_lshl_add_u32 v99, v98, 2, s7
	ds_read_b32 v100, v99
	v_or_b32_e32 v98, s6, v98
	v_ashrrev_i32_e32 v99, 31, v98
	v_lshlrev_b64 v[98:99], 13, v[98:99]
	v_lshl_add_u64 v[98:99], s[8:9], 0, v[98:99]
	s_waitcnt lgkmcnt(0)
	v_mul_f32_e32 v66, v66, v100
	v_mul_f32_e32 v67, v67, v100
	v_mul_f32_e32 v68, v68, v100
	v_mul_f32_e32 v69, v69, v100
	v_lshl_add_u64 v[98:99], v[98:99], 0, s[10:11]
	v_max_f32_e32 v66, 0, v66
	v_max_f32_e32 v67, 0, v67
	v_max_f32_e32 v68, 0, v68
	v_max_f32_e32 v69, 0, v69
	v_lshl_add_u64 v[98:99], v[98:99], 0, v[130:131]
	v_pk_mul_f32 v[66:67], v[66:67], v[66:67]
	v_pk_mul_f32 v[68:69], v[68:69], v[68:69]
	v_lshl_add_u64 v[98:99], v[98:99], 0, v[0:1]
	v_cvt_pk_bf16_f32 v154, v66, v67
	v_cvt_pk_bf16_f32 v155, v68, v69
	s_nop 0
	v_mul_f32_e32 v66, v94, v100
	v_mul_f32_e32 v67, v95, v100
	v_mul_f32_e32 v68, v96, v100
	v_mul_f32_e32 v69, v97, v100
	v_max_f32_e32 v66, 0, v66
	v_max_f32_e32 v67, 0, v67
	v_max_f32_e32 v68, 0, v68
	v_max_f32_e32 v69, 0, v69
	v_pk_mul_f32 v[66:67], v[66:67], v[66:67]
	v_pk_mul_f32 v[68:69], v[68:69], v[68:69]
	v_cvt_pk_bf16_f32 v156, v66, v67
	v_cvt_pk_bf16_f32 v157, v68, v69
	s_nop 0
	v_mul_f32_e32 v66, v86, v100
	v_mul_f32_e32 v67, v87, v100
	v_mul_f32_e32 v68, v88, v100
	v_mul_f32_e32 v69, v89, v100
	v_max_f32_e32 v66, 0, v66
	v_max_f32_e32 v67, 0, v67
	v_max_f32_e32 v68, 0, v68
	v_max_f32_e32 v69, 0, v69
	v_pk_mul_f32 v[66:67], v[66:67], v[66:67]
	v_pk_mul_f32 v[68:69], v[68:69], v[68:69]
	v_cvt_pk_bf16_f32 v158, v66, v67
	v_cvt_pk_bf16_f32 v159, v68, v69
	v_lshl_add_u64 v[206:207], v[98:99], 0, v[204:205]
	s_nop 1
	v_permlane16_swap_b32_e32 v156, v158
	v_permlane16_swap_b32_e32 v157, v159
	global_store_dwordx4 v[206:207], v[156:159], off offset:256
	v_mul_f32_e32 v66, v78, v100
	v_mul_f32_e32 v67, v79, v100
	v_mul_f32_e32 v68, v80, v100
	v_mul_f32_e32 v69, v81, v100
	v_max_f32_e32 v66, 0, v66
	v_max_f32_e32 v67, 0, v67
	v_max_f32_e32 v68, 0, v68
	v_max_f32_e32 v69, 0, v69
	v_pk_mul_f32 v[66:67], v[66:67], v[66:67]
	v_pk_mul_f32 v[68:69], v[68:69], v[68:69]
	v_cvt_pk_bf16_f32 v160, v66, v67
	v_cvt_pk_bf16_f32 v161, v68, v69
	s_nop 0
	v_mul_f32_e32 v66, v70, v100
	v_mul_f32_e32 v67, v71, v100
	v_mul_f32_e32 v68, v72, v100
	v_mul_f32_e32 v69, v73, v100
	v_max_f32_e32 v66, 0, v66
	v_max_f32_e32 v67, 0, v67
	v_max_f32_e32 v68, 0, v68
	v_max_f32_e32 v69, 0, v69
	v_pk_mul_f32 v[66:67], v[66:67], v[66:67]
	v_pk_mul_f32 v[68:69], v[68:69], v[68:69]
	v_cvt_pk_bf16_f32 v162, v66, v67
	v_cvt_pk_bf16_f32 v163, v68, v69
	v_lshl_add_u64 v[206:207], v[98:99], 0, v[204:205]
	s_nop 1
	v_permlane16_swap_b32_e32 v160, v162
	v_permlane16_swap_b32_e32 v161, v163
	global_store_dwordx4 v[206:207], v[160:163], off offset:320
	v_or_b32_e32 v66, 0x80, v132
	v_lshl_add_u32 v67, v66, 2, s7
	ds_read_b32 v68, v67
	v_or_b32_e32 v66, s6, v66
	v_ashrrev_i32_e32 v67, 31, v66
	v_lshlrev_b64 v[66:67], 13, v[66:67]
	v_lshl_add_u64 v[66:67], s[8:9], 0, v[66:67]
	s_waitcnt lgkmcnt(0)
; DI u32 pack2(float a, float b) { f2_t v = {a, b}; bf2_t r = __builtin_convertvector(v, bf2_t); return __builtin_bit_cast(u32, r); }
; DI void ffn1_tile8(const WsPtrs& W, int layer, int mt, int nt, unsigned char* smem) {
;     ...
;       const int tl = bj * 128 + wc * 32 + n * 16 + fr;
;       const float rv = rs[tl];
;       u16* rowp = W.H1 + (size_t)(m0 + tl) * 4096 + n0 + wr * 64 + fq * 4;
; #pragma unroll
;       for (int ai = 0; ai < 2; ++ai)
; #pragma unroll
;         for (int m = 0; m < 4; ++m) {
;           f32x4v v = acc[ai][bj][m][n];
;           float a0 = fmaxf(v.x * rv, 0.f), a1 = fmaxf(v.y * rv, 0.f), a2 = fmaxf(v.z * rv, 0.f), a3 = fmaxf(v.w * rv, 0.f);
;           u32x2 o2; o2.x = pack2(a0 * a0, a1 * a1); o2.y = pack2(a2 * a2, a3 * a3);
;           *(u32x2*)(rowp + ai * 128 + m * 16) = o2;
;         }
	v_mul_f32_e32 v34, v34, v68
	v_mul_f32_e32 v35, v35, v68
	v_mul_f32_e32 v36, v36, v68
	v_mul_f32_e32 v37, v37, v68
	v_lshl_add_u64 v[66:67], v[66:67], 0, s[10:11]
	v_max_f32_e32 v34, 0, v34
	v_max_f32_e32 v35, 0, v35
	v_max_f32_e32 v36, 0, v36
	v_max_f32_e32 v37, 0, v37
	v_lshl_add_u64 v[66:67], v[66:67], 0, v[130:131]
	v_pk_mul_f32 v[34:35], v[34:35], v[34:35]
	v_pk_mul_f32 v[36:37], v[36:37], v[36:37]
	v_lshl_add_u64 v[66:67], v[66:67], 0, v[0:1]
	v_cvt_pk_bf16_f32 v166, v34, v35
	v_cvt_pk_bf16_f32 v167, v36, v37
	s_nop 0
	v_or_b32_e32 v34, 0x90, v132
	v_lshl_add_u32 v35, v34, 2, s7
	v_or_b32_e32 v34, s6, v34
	ds_read_b32 v36, v35
	v_ashrrev_i32_e32 v35, 31, v34
	v_lshlrev_b64 v[34:35], 13, v[34:35]
	v_lshl_add_u64 v[34:35], s[8:9], 0, v[34:35]
	v_lshl_add_u64 v[34:35], v[34:35], 0, s[10:11]
	v_lshl_add_u64 v[34:35], v[34:35], 0, v[130:131]
	v_lshl_add_u64 v[34:35], v[34:35], 0, v[0:1]
	s_waitcnt lgkmcnt(0)
	v_mul_f32_e32 v0, v30, v36
	v_max_f32_e32 v30, 0, v0
	v_mul_f32_e32 v0, v31, v36
	v_max_f32_e32 v31, 0, v0
	v_mul_f32_e32 v0, v32, v36
	v_max_f32_e32 v32, 0, v0
	v_mul_f32_e32 v0, v33, v36
	v_max_f32_e32 v33, 0, v0
	v_mul_f32_e32 v0, v26, v36
	v_max_f32_e32 v26, 0, v0
	v_mul_f32_e32 v0, v27, v36
	v_max_f32_e32 v27, 0, v0
	v_mul_f32_e32 v0, v28, v36
	v_max_f32_e32 v28, 0, v0
	v_mul_f32_e32 v0, v29, v36
	v_max_f32_e32 v29, 0, v0
	v_mul_f32_e32 v0, v18, v36
	v_max_f32_e32 v18, 0, v0
	v_mul_f32_e32 v0, v19, v36
	v_max_f32_e32 v19, 0, v0
	v_mul_f32_e32 v0, v20, v36
	v_max_f32_e32 v20, 0, v0
	v_mul_f32_e32 v0, v21, v36
	v_max_f32_e32 v21, 0, v0
	v_mul_f32_e32 v0, v10, v36
	v_max_f32_e32 v10, 0, v0
	v_mul_f32_e32 v0, v11, v36
	v_max_f32_e32 v11, 0, v0
	v_mul_f32_e32 v0, v12, v36
	v_max_f32_e32 v12, 0, v0
	v_mul_f32_e32 v0, v13, v36
	v_max_f32_e32 v13, 0, v0
	v_pk_mul_f32 v[10:11], v[10:11], v[10:11]
	v_pk_mul_f32 v[12:13], v[12:13], v[12:13]
	v_cvt_pk_bf16_f32 v170, v10, v11
	v_cvt_pk_bf16_f32 v171, v12, v13
	v_mul_f32_e32 v0, v22, v36
	s_nop 0
	v_max_f32_e32 v10, 0, v0
	v_mul_f32_e32 v0, v23, v36
	v_max_f32_e32 v11, 0, v0
	v_mul_f32_e32 v0, v24, v36
	v_max_f32_e32 v12, 0, v0
	v_mul_f32_e32 v0, v25, v36
	v_mul_f32_e32 v38, v38, v68
	v_mul_f32_e32 v39, v39, v68
	v_mul_f32_e32 v40, v40, v68
	v_mul_f32_e32 v41, v41, v68
	v_max_f32_e32 v13, 0, v0
	v_max_f32_e32 v38, 0, v38
	v_max_f32_e32 v39, 0, v39
	v_max_f32_e32 v40, 0, v40
	v_max_f32_e32 v41, 0, v41
	v_pk_mul_f32 v[10:11], v[10:11], v[10:11]
	v_pk_mul_f32 v[12:13], v[12:13], v[12:13]
	v_pk_mul_f32 v[38:39], v[38:39], v[38:39]
	v_pk_mul_f32 v[40:41], v[40:41], v[40:41]
	v_cvt_pk_bf16_f32 v172, v10, v11
	v_cvt_pk_bf16_f32 v173, v12, v13
	v_mul_f32_e32 v0, v14, v36
	v_cvt_pk_bf16_f32 v178, v38, v39
	v_cvt_pk_bf16_f32 v179, v40, v41
	s_nop 0
	v_max_f32_e32 v10, 0, v0
	v_mul_f32_e32 v0, v15, v36
	s_nop 0
	v_mul_f32_e32 v38, v58, v68
	v_mul_f32_e32 v39, v59, v68
	v_mul_f32_e32 v40, v60, v68
	v_mul_f32_e32 v41, v61, v68
	v_max_f32_e32 v11, 0, v0
	v_mul_f32_e32 v0, v16, v36
	v_max_f32_e32 v38, 0, v38
	v_max_f32_e32 v39, 0, v39
	v_max_f32_e32 v40, 0, v40
	v_max_f32_e32 v41, 0, v41
	v_max_f32_e32 v12, 0, v0
	v_mul_f32_e32 v0, v17, v36
	v_pk_mul_f32 v[38:39], v[38:39], v[38:39]
	v_pk_mul_f32 v[40:41], v[40:41], v[40:41]
	v_max_f32_e32 v13, 0, v0
	v_mul_f32_e32 v0, v6, v36
	v_cvt_pk_bf16_f32 v180, v38, v39
	v_cvt_pk_bf16_f32 v181, v40, v41
	v_max_f32_e32 v6, 0, v0
	v_mul_f32_e32 v0, v7, v36
	s_nop 0
	v_mul_f32_e32 v38, v50, v68
	v_mul_f32_e32 v39, v51, v68
	v_mul_f32_e32 v40, v52, v68
	v_mul_f32_e32 v41, v53, v68
	v_max_f32_e32 v7, 0, v0
	v_mul_f32_e32 v0, v8, v36
	v_max_f32_e32 v38, 0, v38
	v_max_f32_e32 v39, 0, v39
	v_max_f32_e32 v40, 0, v40
	v_max_f32_e32 v41, 0, v41
	v_max_f32_e32 v8, 0, v0
	v_mul_f32_e32 v0, v9, v36
	v_pk_mul_f32 v[38:39], v[38:39], v[38:39]
	v_pk_mul_f32 v[40:41], v[40:41], v[40:41]
	v_max_f32_e32 v9, 0, v0
	v_mul_f32_e32 v0, v2, v36
	v_cvt_pk_bf16_f32 v182, v38, v39
	v_cvt_pk_bf16_f32 v183, v40, v41
	v_max_f32_e32 v2, 0, v0
	v_mul_f32_e32 v0, v3, v36
	v_mul_f32_e32 v122, v122, v136
	v_mul_f32_e32 v123, v123, v136
	v_mul_f32_e32 v124, v124, v136
	v_mul_f32_e32 v125, v125, v136
	v_mul_f32_e32 v114, v114, v136
	v_mul_f32_e32 v115, v115, v136
	v_mul_f32_e32 v116, v116, v136
	v_mul_f32_e32 v117, v117, v136
	v_mul_f32_e32 v106, v106, v136
	v_mul_f32_e32 v107, v107, v136
	v_mul_f32_e32 v108, v108, v136
	v_mul_f32_e32 v109, v109, v136
	v_mul_f32_e32 v90, v90, v100
	v_mul_f32_e32 v91, v91, v100
	v_mul_f32_e32 v92, v92, v100
	v_mul_f32_e32 v93, v93, v100
	v_mul_f32_e32 v82, v82, v100
	v_mul_f32_e32 v83, v83, v100
	v_mul_f32_e32 v84, v84, v100
	v_mul_f32_e32 v85, v85, v100
	v_mul_f32_e32 v74, v74, v100
	v_mul_f32_e32 v75, v75, v100
	v_mul_f32_e32 v76, v76, v100
	v_mul_f32_e32 v77, v77, v100
	v_mul_f32_e32 v62, v62, v68
	v_mul_f32_e32 v63, v63, v68
	v_mul_f32_e32 v64, v64, v68
	v_mul_f32_e32 v65, v65, v68
	v_mul_f32_e32 v54, v54, v68
	v_mul_f32_e32 v55, v55, v68
	v_mul_f32_e32 v56, v56, v68
	v_mul_f32_e32 v57, v57, v68
	v_mul_f32_e32 v46, v46, v68
	v_mul_f32_e32 v47, v47, v68
	v_mul_f32_e32 v48, v48, v68
	v_mul_f32_e32 v49, v49, v68
	v_lshl_add_u64 v[206:207], v[66:67], 0, v[204:205]
	s_nop 1
	v_permlane16_swap_b32_e32 v180, v182
	v_permlane16_swap_b32_e32 v181, v183
	global_store_dwordx4 v[206:207], v[180:183], off offset:256
	v_mul_f32_e32 v38, v42, v68
	v_mul_f32_e32 v39, v43, v68
	v_mul_f32_e32 v40, v44, v68
	v_mul_f32_e32 v41, v45, v68
	v_max_f32_e32 v3, 0, v0
	v_mul_f32_e32 v0, v4, v36
	v_max_f32_e32 v122, 0, v122
	v_max_f32_e32 v123, 0, v123
	v_max_f32_e32 v124, 0, v124
	v_max_f32_e32 v125, 0, v125
; DI u32 pack2(float a, float b) { f2_t v = {a, b}; bf2_t r = __builtin_convertvector(v, bf2_t); return __builtin_bit_cast(u32, r); }
; DI void ffn1_tile8(const WsPtrs& W, int layer, int mt, int nt, unsigned char* smem) {
;     ...
;       const int tl = bj * 128 + wc * 32 + n * 16 + fr;
;       const float rv = rs[tl];
;       u16* rowp = W.H1 + (size_t)(m0 + tl) * 4096 + n0 + wr * 64 + fq * 4;
; #pragma unroll
;       for (int ai = 0; ai < 2; ++ai)
; #pragma unroll
;         for (int m = 0; m < 4; ++m) {
;           f32x4v v = acc[ai][bj][m][n];
;           float a0 = fmaxf(v.x * rv, 0.f), a1 = fmaxf(v.y * rv, 0.f), a2 = fmaxf(v.z * rv, 0.f), a3 = fmaxf(v.w * rv, 0.f);
;           u32x2 o2; o2.x = pack2(a0 * a0, a1 * a1); o2.y = pack2(a2 * a2, a3 * a3);
;           *(u32x2*)(rowp + ai * 128 + m * 16) = o2;
;         }
	v_max_f32_e32 v114, 0, v114
	v_max_f32_e32 v115, 0, v115
	v_max_f32_e32 v116, 0, v116
	v_max_f32_e32 v117, 0, v117
	v_max_f32_e32 v106, 0, v106
	v_max_f32_e32 v107, 0, v107
	v_max_f32_e32 v108, 0, v108
	v_max_f32_e32 v109, 0, v109
	v_max_f32_e32 v90, 0, v90
	v_max_f32_e32 v91, 0, v91
	v_max_f32_e32 v92, 0, v92
	v_max_f32_e32 v93, 0, v93
	v_max_f32_e32 v82, 0, v82
	v_max_f32_e32 v83, 0, v83
	v_max_f32_e32 v84, 0, v84
	v_max_f32_e32 v85, 0, v85
	v_max_f32_e32 v74, 0, v74
	v_max_f32_e32 v75, 0, v75
	v_max_f32_e32 v76, 0, v76
	v_max_f32_e32 v77, 0, v77
	v_max_f32_e32 v62, 0, v62
	v_max_f32_e32 v63, 0, v63
	v_max_f32_e32 v64, 0, v64
	v_max_f32_e32 v65, 0, v65
	v_max_f32_e32 v54, 0, v54
	v_max_f32_e32 v55, 0, v55
	v_max_f32_e32 v56, 0, v56
	v_max_f32_e32 v57, 0, v57
	v_max_f32_e32 v46, 0, v46
	v_max_f32_e32 v47, 0, v47
	v_max_f32_e32 v48, 0, v48
	v_max_f32_e32 v49, 0, v49
	v_max_f32_e32 v38, 0, v38
	v_max_f32_e32 v39, 0, v39
	v_max_f32_e32 v40, 0, v40
	v_max_f32_e32 v41, 0, v41
	v_max_f32_e32 v4, 0, v0
	v_mul_f32_e32 v0, v5, v36
	v_pk_mul_f32 v[122:123], v[122:123], v[122:123]
	v_pk_mul_f32 v[124:125], v[124:125], v[124:125]
	v_pk_mul_f32 v[114:115], v[114:115], v[114:115]
	v_pk_mul_f32 v[116:117], v[116:117], v[116:117]
	v_pk_mul_f32 v[106:107], v[106:107], v[106:107]
	v_pk_mul_f32 v[108:109], v[108:109], v[108:109]
	v_pk_mul_f32 v[90:91], v[90:91], v[90:91]
	v_pk_mul_f32 v[92:93], v[92:93], v[92:93]
	v_pk_mul_f32 v[82:83], v[82:83], v[82:83]
	v_pk_mul_f32 v[84:85], v[84:85], v[84:85]
	v_pk_mul_f32 v[74:75], v[74:75], v[74:75]
	v_pk_mul_f32 v[76:77], v[76:77], v[76:77]
	v_pk_mul_f32 v[62:63], v[62:63], v[62:63]
	v_pk_mul_f32 v[64:65], v[64:65], v[64:65]
	v_pk_mul_f32 v[54:55], v[54:55], v[54:55]
	v_pk_mul_f32 v[56:57], v[56:57], v[56:57]
	v_pk_mul_f32 v[46:47], v[46:47], v[46:47]
	v_pk_mul_f32 v[48:49], v[48:49], v[48:49]
	v_pk_mul_f32 v[38:39], v[38:39], v[38:39]
	v_pk_mul_f32 v[40:41], v[40:41], v[40:41]
	v_pk_mul_f32 v[30:31], v[30:31], v[30:31]
	v_pk_mul_f32 v[32:33], v[32:33], v[32:33]
	v_pk_mul_f32 v[26:27], v[26:27], v[26:27]
	v_pk_mul_f32 v[28:29], v[28:29], v[28:29]
	v_pk_mul_f32 v[18:19], v[18:19], v[18:19]
	v_pk_mul_f32 v[20:21], v[20:21], v[20:21]
	v_pk_mul_f32 v[10:11], v[10:11], v[10:11]
	v_pk_mul_f32 v[12:13], v[12:13], v[12:13]
	v_pk_mul_f32 v[6:7], v[6:7], v[6:7]
	v_pk_mul_f32 v[8:9], v[8:9], v[8:9]
	v_max_f32_e32 v5, 0, v0
	v_pk_mul_f32 v[2:3], v[2:3], v[2:3]
	v_cvt_pk_bf16_f32 v184, v122, v123
	v_cvt_pk_bf16_f32 v185, v124, v125
	v_cvt_pk_bf16_f32 v186, v114, v115
	v_cvt_pk_bf16_f32 v187, v116, v117
	v_cvt_pk_bf16_f32 v140, v106, v107
	v_cvt_pk_bf16_f32 v141, v108, v109
	v_cvt_pk_bf16_f32 v188, v90, v91
	v_cvt_pk_bf16_f32 v189, v92, v93
	v_cvt_pk_bf16_f32 v190, v82, v83
	v_cvt_pk_bf16_f32 v191, v84, v85
	v_cvt_pk_bf16_f32 v152, v74, v75
	v_cvt_pk_bf16_f32 v153, v76, v77
	v_cvt_pk_bf16_f32 v192, v62, v63
	v_cvt_pk_bf16_f32 v193, v64, v65
	v_cvt_pk_bf16_f32 v194, v54, v55
	v_cvt_pk_bf16_f32 v195, v56, v57
	v_cvt_pk_bf16_f32 v176, v46, v47
	v_cvt_pk_bf16_f32 v177, v48, v49
	v_cvt_pk_bf16_f32 v164, v38, v39
	v_cvt_pk_bf16_f32 v165, v40, v41
	v_cvt_pk_bf16_f32 v196, v30, v31
	v_cvt_pk_bf16_f32 v197, v32, v33
	v_cvt_pk_bf16_f32 v198, v26, v27
	v_cvt_pk_bf16_f32 v199, v28, v29
	v_cvt_pk_bf16_f32 v168, v18, v19
	v_cvt_pk_bf16_f32 v169, v20, v21
	v_cvt_pk_bf16_f32 v174, v10, v11
	v_cvt_pk_bf16_f32 v175, v12, v13
	v_cvt_pk_bf16_f32 v6, v6, v7
	v_cvt_pk_bf16_f32 v7, v8, v9
	v_cvt_pk_bf16_f32 v2, v2, v3
	v_pk_mul_f32 v[4:5], v[4:5], v[4:5]
	s_nop 0
	v_lshl_add_u64 v[206:207], v[134:135], 0, v[204:205]
	s_nop 1
	v_permlane16_swap_b32_e32 v184, v186
	v_permlane16_swap_b32_e32 v185, v187
	global_store_dwordx4 v[206:207], v[184:187], off
	v_lshl_add_u64 v[206:207], v[134:135], 0, v[204:205]
	s_nop 1
	v_permlane16_swap_b32_e32 v140, v142
	v_permlane16_swap_b32_e32 v141, v143
	global_store_dwordx4 v[206:207], v[140:143], off offset:64
	s_nop 0
	v_lshl_add_u64 v[206:207], v[98:99], 0, v[204:205]
	s_nop 1
	v_permlane16_swap_b32_e32 v188, v190
	v_permlane16_swap_b32_e32 v189, v191
	global_store_dwordx4 v[206:207], v[188:191], off
	v_lshl_add_u64 v[206:207], v[98:99], 0, v[204:205]
	s_nop 1
	v_permlane16_swap_b32_e32 v152, v154
	v_permlane16_swap_b32_e32 v153, v155
	global_store_dwordx4 v[206:207], v[152:155], off offset:64
	s_nop 0
	v_lshl_add_u64 v[206:207], v[66:67], 0, v[204:205]
	s_nop 1
	v_permlane16_swap_b32_e32 v192, v194
	v_permlane16_swap_b32_e32 v193, v195
	global_store_dwordx4 v[206:207], v[192:195], off
	v_lshl_add_u64 v[206:207], v[66:67], 0, v[204:205]
	s_nop 1
	v_permlane16_swap_b32_e32 v176, v178
	v_permlane16_swap_b32_e32 v177, v179
	global_store_dwordx4 v[206:207], v[176:179], off offset:64
	v_lshl_add_u64 v[206:207], v[66:67], 0, v[204:205]
	s_nop 1
	v_permlane16_swap_b32_e32 v164, v166
	v_permlane16_swap_b32_e32 v165, v167
	global_store_dwordx4 v[206:207], v[164:167], off offset:320
	s_nop 0
	v_lshl_add_u64 v[206:207], v[34:35], 0, v[204:205]
	s_nop 1
	v_permlane16_swap_b32_e32 v196, v198
	v_permlane16_swap_b32_e32 v197, v199
	global_store_dwordx4 v[206:207], v[196:199], off
	v_lshl_add_u64 v[206:207], v[34:35], 0, v[204:205]
	s_nop 1
	v_permlane16_swap_b32_e32 v168, v170
	v_permlane16_swap_b32_e32 v169, v171
	global_store_dwordx4 v[206:207], v[168:171], off offset:64
	v_lshl_add_u64 v[206:207], v[34:35], 0, v[204:205]
	s_nop 1
	v_permlane16_swap_b32_e32 v172, v174
	v_permlane16_swap_b32_e32 v173, v175
	global_store_dwordx4 v[206:207], v[172:175], off offset:256
	global_store_dwordx2 v[34:35], v[6:7], off offset:320

; DI u32 pack2(float a, float b) { f2_t v = {a, b}; bf2_t r = __builtin_convertvector(v, bf2_t); return __builtin_bit_cast(u32, r); }
; DI void pp_tile8(const WsPtrs& W, int layer, int mt, int nt, unsigned char* smem) {
;     ...
;   for (int bj = 0; bj < 2; ++bj)
; #pragma unroll
;     for (int n = 0; n < 2; ++n) {
;       u16* rowp = W.MERGED + (size_t)(m0 + bj * 128 + wc * 32 + n * 16 + fr) * 1024 + n0 + wr * 64 + fq * 4;
; #pragma unroll
;       for (int ai = 0; ai < 2; ++ai)
; #pragma unroll
;         for (int m = 0; m < 4; ++m) {
;           f32x4v a = acc[ai][bj][m][n];
;           u32x2 o2; o2.x = pack2(a.x, a.y); o2.y = pack2(a.z, a.w);
;           *(u32x2*)(rowp + ai * 128 + m * 16) = o2;
;         }
.LBB0_912:
	s_or_b64 exec, exec, s[10:11]
	v_mbcnt_lo_u32_b32 v204, -1, 0
	v_mbcnt_hi_u32_b32 v204, -1, v204
	v_bfe_u32 v204, v204, 4, 1
	v_mul_u32_u24_e32 v204, 24, v204
	v_mov_b32_e32 v205, 0
	v_mov_b32_e32 v0, v250
	s_add_u32 s10, s62, s53
	v_lshrrev_b32_e32 v136, 1, v0
	v_and_b32_e32 v130, 15, v0
	v_and_b32_e32 v131, 0x60, v136
	v_or3_b32 v130, v130, v131, s8
	v_ashrrev_i32_e32 v0, 2, v0
	v_ashrrev_i32_e32 v131, 31, v130
	s_addc_u32 s11, s63, s70
	v_and_b32_e32 v132, 0xffffffc0, v0
	v_lshlrev_b64 v[134:135], 11, v[130:131]
	v_ashrrev_i32_e32 v133, 31, v132
	v_lshl_add_u64 v[134:135], s[10:11], 0, v[134:135]
	s_lshl_b64 s[6:7], s[6:7], 1
	v_lshl_add_u64 v[134:135], v[134:135], 0, s[6:7]
	v_lshlrev_b64 v[132:133], 1, v[132:133]
	v_lshl_add_u64 v[134:135], v[134:135], 0, v[132:133]
	v_and_b32_e32 v0, 24, v136
	v_lshl_add_u64 v[134:135], v[134:135], 0, v[0:1]
	v_cvt_pk_bf16_f32 v142, v98, v99
	v_cvt_pk_bf16_f32 v143, v100, v101
	s_nop 0
	v_cvt_pk_bf16_f32 v144, v126, v127
	v_cvt_pk_bf16_f32 v145, v128, v129
	s_nop 0
	v_cvt_pk_bf16_f32 v146, v122, v123
	v_cvt_pk_bf16_f32 v147, v124, v125
	v_lshl_add_u64 v[206:207], v[134:135], 0, v[204:205]
	s_nop 1
	v_permlane16_swap_b32_e32 v144, v146
	v_permlane16_swap_b32_e32 v145, v147
	global_store_dwordx4 v[206:207], v[144:147], off offset:256
	v_cvt_pk_bf16_f32 v148, v118, v119
	v_cvt_pk_bf16_f32 v149, v120, v121
	s_nop 0
	v_cvt_pk_bf16_f32 v150, v114, v115
	v_cvt_pk_bf16_f32 v151, v116, v117
	v_lshl_add_u64 v[206:207], v[134:135], 0, v[204:205]
	s_nop 1
	v_permlane16_swap_b32_e32 v148, v150
	v_permlane16_swap_b32_e32 v149, v151
	global_store_dwordx4 v[206:207], v[148:151], off offset:320
	v_or_b32_e32 v98, 16, v130
	v_ashrrev_i32_e32 v99, 31, v98
	v_lshlrev_b64 v[98:99], 11, v[98:99]
	v_lshl_add_u64 v[98:99], s[10:11], 0, v[98:99]
	v_lshl_add_u64 v[98:99], v[98:99], 0, s[6:7]
	v_lshl_add_u64 v[98:99], v[98:99], 0, v[132:133]
	v_lshl_add_u64 v[98:99], v[98:99], 0, v[0:1]
	v_cvt_pk_bf16_f32 v154, v50, v51
	v_cvt_pk_bf16_f32 v155, v52, v53
	s_nop 0
	v_cvt_pk_bf16_f32 v156, v94, v95
	v_cvt_pk_bf16_f32 v157, v96, v97
	s_nop 0
	v_cvt_pk_bf16_f32 v158, v90, v91
	v_cvt_pk_bf16_f32 v159, v92, v93
	v_lshl_add_u64 v[206:207], v[98:99], 0, v[204:205]
	s_nop 1
	v_permlane16_swap_b32_e32 v156, v158
	v_permlane16_swap_b32_e32 v157, v159
	global_store_dwordx4 v[206:207], v[156:159], off offset:256
	v_cvt_pk_bf16_f32 v160, v86, v87
	v_cvt_pk_bf16_f32 v161, v88, v89
	s_nop 0
	v_cvt_pk_bf16_f32 v162, v82, v83
	v_cvt_pk_bf16_f32 v163, v84, v85
	v_lshl_add_u64 v[206:207], v[98:99], 0, v[204:205]
	s_nop 1
	v_permlane16_swap_b32_e32 v160, v162
	v_permlane16_swap_b32_e32 v161, v163
	global_store_dwordx4 v[206:207], v[160:163], off offset:320
	v_or_b32_e32 v50, 0x80, v130
	v_ashrrev_i32_e32 v51, 31, v50
	v_lshlrev_b64 v[50:51], 11, v[50:51]
	v_lshl_add_u64 v[50:51], s[10:11], 0, v[50:51]
	v_lshl_add_u64 v[50:51], v[50:51], 0, s[6:7]
	v_lshl_add_u64 v[50:51], v[50:51], 0, v[132:133]
	v_lshl_add_u64 v[50:51], v[50:51], 0, v[0:1]
	v_cvt_pk_bf16_f32 v166, v34, v35
	v_cvt_pk_bf16_f32 v167, v36, v37
	s_nop 0
	v_cvt_pk_bf16_f32 v168, v78, v79
	v_cvt_pk_bf16_f32 v169, v80, v81
	s_nop 0
	v_cvt_pk_bf16_f32 v170, v74, v75
	v_cvt_pk_bf16_f32 v171, v76, v77
	v_lshl_add_u64 v[206:207], v[50:51], 0, v[204:205]
	s_nop 1
	v_permlane16_swap_b32_e32 v168, v170
	v_permlane16_swap_b32_e32 v169, v171
	global_store_dwordx4 v[206:207], v[168:171], off offset:256
	v_cvt_pk_bf16_f32 v172, v70, v71
	v_cvt_pk_bf16_f32 v173, v72, v73
	s_nop 0
	v_cvt_pk_bf16_f32 v174, v62, v63
	v_cvt_pk_bf16_f32 v175, v64, v65
	v_lshl_add_u64 v[206:207], v[50:51], 0, v[204:205]
	s_nop 1
	v_permlane16_swap_b32_e32 v172, v174
	v_permlane16_swap_b32_e32 v173, v175
	global_store_dwordx4 v[206:207], v[172:175], off offset:320
	v_or_b32_e32 v34, 0x90, v130
	v_ashrrev_i32_e32 v35, 31, v34
	v_lshlrev_b64 v[34:35], 11, v[34:35]
	v_lshl_add_u64 v[34:35], s[10:11], 0, v[34:35]
	v_lshl_add_u64 v[34:35], v[34:35], 0, s[6:7]
	v_lshl_add_u64 v[34:35], v[34:35], 0, v[132:133]
	v_lshl_add_u64 v[34:35], v[34:35], 0, v[0:1]
	v_cvt_pk_bf16_f32 v178, v6, v7
	v_cvt_pk_bf16_f32 v179, v8, v9
	s_nop 0
	v_cvt_pk_bf16_f32 v180, v30, v31
	v_cvt_pk_bf16_f32 v181, v32, v33
	s_nop 0
	v_cvt_pk_bf16_f32 v182, v26, v27
	v_cvt_pk_bf16_f32 v183, v28, v29
	v_cvt_pk_bf16_f32 v184, v110, v111
	v_cvt_pk_bf16_f32 v185, v112, v113
	v_cvt_pk_bf16_f32 v186, v106, v107
	v_cvt_pk_bf16_f32 v187, v108, v109
	v_cvt_pk_bf16_f32 v140, v102, v103
	v_cvt_pk_bf16_f32 v141, v104, v105
	v_cvt_pk_bf16_f32 v188, v66, v67
	v_cvt_pk_bf16_f32 v189, v68, v69
	v_cvt_pk_bf16_f32 v190, v58, v59
	v_cvt_pk_bf16_f32 v191, v60, v61
	v_cvt_pk_bf16_f32 v152, v54, v55
	v_cvt_pk_bf16_f32 v153, v56, v57
	v_cvt_pk_bf16_f32 v192, v46, v47
	v_cvt_pk_bf16_f32 v193, v48, v49
	v_cvt_pk_bf16_f32 v194, v42, v43
	v_cvt_pk_bf16_f32 v195, v44, v45
	v_cvt_pk_bf16_f32 v164, v38, v39
	v_cvt_pk_bf16_f32 v165, v40, v41
	v_cvt_pk_bf16_f32 v196, v18, v19
	v_cvt_pk_bf16_f32 v197, v20, v21
	v_cvt_pk_bf16_f32 v198, v14, v15
	v_cvt_pk_bf16_f32 v199, v16, v17
	v_cvt_pk_bf16_f32 v176, v10, v11
	v_cvt_pk_bf16_f32 v177, v12, v13
	v_lshl_add_u64 v[206:207], v[34:35], 0, v[204:205]
	s_nop 1
	v_permlane16_swap_b32_e32 v180, v182
	v_permlane16_swap_b32_e32 v181, v183
	global_store_dwordx4 v[206:207], v[180:183], off offset:256
	v_cvt_pk_bf16_f32 v6, v22, v23
	v_cvt_pk_bf16_f32 v7, v24, v25
	v_cvt_pk_bf16_f32 v2, v2, v3
	s_mov_b64 s[6:7], 0
	s_nop 0
	v_lshl_add_u64 v[206:207], v[134:135], 0, v[204:205]
	s_nop 1
	v_permlane16_swap_b32_e32 v184, v186
	v_permlane16_swap_b32_e32 v185, v187
	global_store_dwordx4 v[206:207], v[184:187], off
	v_lshl_add_u64 v[206:207], v[134:135], 0, v[204:205]
	s_nop 1
	v_permlane16_swap_b32_e32 v140, v142
	v_permlane16_swap_b32_e32 v141, v143
	global_store_dwordx4 v[206:207], v[140:143], off offset:64
	s_nop 0
	v_lshl_add_u64 v[206:207], v[98:99], 0, v[204:205]
	s_nop 1
	v_permlane16_swap_b32_e32 v188, v190
	v_permlane16_swap_b32_e32 v189, v191
	global_store_dwordx4 v[206:207], v[188:191], off
	v_lshl_add_u64 v[206:207], v[98:99], 0, v[204:205]
	s_nop 1
	v_permlane16_swap_b32_e32 v152, v154
	v_permlane16_swap_b32_e32 v153, v155
	global_store_dwordx4 v[206:207], v[152:155], off offset:64
	s_nop 0
	v_lshl_add_u64 v[206:207], v[50:51], 0, v[204:205]
	s_nop 1
	v_permlane16_swap_b32_e32 v192, v194
	v_permlane16_swap_b32_e32 v193, v195
	global_store_dwordx4 v[206:207], v[192:195], off
	v_lshl_add_u64 v[206:207], v[50:51], 0, v[204:205]
	s_nop 1
	v_permlane16_swap_b32_e32 v164, v166
	v_permlane16_swap_b32_e32 v165, v167
	global_store_dwordx4 v[206:207], v[164:167], off offset:64
	s_nop 0
	v_lshl_add_u64 v[206:207], v[34:35], 0, v[204:205]
	s_nop 1
	v_permlane16_swap_b32_e32 v196, v198
	v_permlane16_swap_b32_e32 v197, v199
	global_store_dwordx4 v[206:207], v[196:199], off
	v_lshl_add_u64 v[206:207], v[34:35], 0, v[204:205]
	s_nop 1
	v_permlane16_swap_b32_e32 v176, v178
	v_permlane16_swap_b32_e32 v177, v179
	global_store_dwordx4 v[206:207], v[176:179], off offset:64
	global_store_dwordx2 v[34:35], v[6:7], off offset:320
